# select_row post-search: membership nibbles via v_cmp + v_addc (2n + carry), tie-path mask compares moved behind the exact-hit branch
# speedup vs baseline: 1.0029x; 1.0011x over previous
; DI void select_row(const float* SC, unsigned* dmask, int b, int t, int lane) {
;     ...
;     int cgt = 0, cge = 256;
;     if (!hit) { cge = 0;
; #pragma unroll
;     for (int k = 0; k < 8; ++k) if (k < nch) {
; #pragma unroll
;         for (int e = 0; e < 4; ++e) { cgt += __popcll(__ballot(u[k][e] > T)); cge += __popcll(__ballot(u[k][e] >= T)); }
;     }
;     }
.LBB0_582:
	s_mov_b32 s57, s92
	s_mov_b32 s56, s95
	s_mov_b64 s[66:67], s[96:97]
	s_and_b64 vcc, exec, s[8:9]
	s_waitcnt lgkmcnt(0)
	s_cbranch_vccnz .LBB0_589
	v_cmp_gt_u32_e64 s[96:97], v11, v2
	v_cmp_ge_u32_e64 s[10:11], v11, v2
	v_cmp_gt_u32_e64 s[8:9], v10, v2
	v_cmp_gt_u32_e64 s[94:95], v121, v2
	v_cmp_gt_u32_e64 s[92:93], v9, v2
	v_cmp_gt_u32_e64 s[90:91], v7, v2
	v_cmp_ge_u32_e64 s[88:89], v7, v2
	v_cmp_gt_u32_e64 s[86:87], v6, v2
	v_cmp_gt_u32_e64 s[84:85], v8, v2
	v_cmp_gt_u32_e64 s[80:81], v5, v2
	v_cmp_ge_u32_e32 vcc, v10, v2
	s_bcnt1_i32_b64 s14, s[96:97]
	s_bcnt1_i32_b64 s10, s[10:11]
	s_bcnt1_i32_b64 s8, s[8:9]
	s_bcnt1_i32_b64 s9, vcc
	s_add_i32 s8, s8, s14
	s_add_i32 s9, s9, s10
	s_bcnt1_i32_b64 s10, s[94:95]
	v_cmp_ge_u32_e32 vcc, v121, v2
	s_add_i32 s8, s8, s10
	s_bcnt1_i32_b64 s10, vcc
	s_add_i32 s9, s9, s10
	s_bcnt1_i32_b64 s10, s[92:93]
	v_cmp_ge_u32_e32 vcc, v9, v2
	s_add_i32 s8, s8, s10
	s_bcnt1_i32_b64 s10, vcc
	s_add_i32 s9, s9, s10
	s_bcnt1_i32_b64 s10, s[90:91]
	s_add_i32 s8, s8, s10
	s_bcnt1_i32_b64 s10, s[88:89]
	s_add_i32 s9, s9, s10
	s_bcnt1_i32_b64 s10, s[86:87]
	v_cmp_ge_u32_e32 vcc, v6, v2
	s_add_i32 s8, s8, s10
	s_bcnt1_i32_b64 s10, vcc
	s_add_i32 s9, s9, s10
	s_bcnt1_i32_b64 s10, s[84:85]
	v_cmp_ge_u32_e32 vcc, v8, v2
	s_add_i32 s8, s8, s10
	s_bcnt1_i32_b64 s10, vcc
	s_add_i32 s9, s9, s10
	s_bcnt1_i32_b64 s10, s[80:81]
	v_cmp_ge_u32_e32 vcc, v5, v2
	s_add_i32 s8, s8, s10
	s_bcnt1_i32_b64 s10, vcc
	s_and_b64 vcc, exec, s[82:83]
	s_add_i32 s9, s9, s10
	s_cbranch_vccnz .LBB0_590
	v_cmp_gt_u32_e32 vcc, v33, v2
	s_bcnt1_i32_b64 s10, vcc
	v_cmp_ge_u32_e32 vcc, v33, v2
	s_add_i32 s8, s8, s10
	s_bcnt1_i32_b64 s10, vcc
	v_cmp_gt_u32_e32 vcc, v41, v2
	s_add_i32 s9, s9, s10
	s_bcnt1_i32_b64 s10, vcc
	v_cmp_ge_u32_e32 vcc, v41, v2
	s_add_i32 s8, s8, s10
	s_bcnt1_i32_b64 s10, vcc
	v_cmp_gt_u32_e32 vcc, v32, v2
	s_add_i32 s9, s9, s10
	s_bcnt1_i32_b64 s10, vcc
	v_cmp_ge_u32_e32 vcc, v32, v2
	s_add_i32 s8, s8, s10
	s_bcnt1_i32_b64 s10, vcc
	v_cmp_gt_u32_e32 vcc, v42, v2
	s_add_i32 s9, s9, s10
	s_bcnt1_i32_b64 s10, vcc
	v_cmp_ge_u32_e32 vcc, v42, v2
	s_add_i32 s8, s8, s10
	s_bcnt1_i32_b64 s10, vcc
	s_add_i32 s9, s9, s10
	s_mov_b64 s[96:97], s[66:67]
	s_mov_b32 s95, s56
	s_andn2_b64 vcc, exec, s[54:55]
	s_cbranch_vccz .LBB0_591

; DI void select_row(const float* SC, unsigned* dmask, int b, int t, int lane) {
;     ...
;     for (int k = 0; k < 8; ++k) {
;         unsigned nib = 0u;
;         if (k < nch) {
;             if (exact) {
; #pragma unroll
;                 for (int e = 0; e < 4; ++e) nib |= (u[k][e] >= T ? 1u : 0u) << e;
;             } else {
;                 unsigned long long bm[4]; int lanes_before = 0, tot = 0;
; #pragma unroll
;                 for (int e = 0; e < 4; ++e) { bm[e] = __ballot(u[k][e] == T); lanes_before += __popcll(bm[e] & ltmask); tot += __popcll(bm[e]); }
;                 int rank = tie_before + lanes_before;
; #pragma unroll
;                 for (int e = 0; e < 4; ++e) { const bool eq = (u[k][e] == T); const bool s = (u[k][e] > T) || (eq && rank < need); nib |= (s ? 1u : 0u) << e; rank += eq ? 1 : 0; }
;                 tie_before += tot;
;             }
;         }
;         unsigned val = nib << (4 * (lane & 7));
;         val |= (unsigned)__builtin_amdgcn_update_dpp(0, (int)val, 0x101, 0xf, 0xf, true); val |= (unsigned)__builtin_amdgcn_update_dpp(0, (int)val, 0x102, 0xf, 0xf, true); val |= (unsigned)__builtin_amdgcn_update_dpp(0, (int)val, 0x104, 0xf, 0xf, true);
;         if ((lane & 7) == 0) dm[8 * k + (lane >> 3)] = val;
.LBB0_599:
	s_andn2_b64 vcc, exec, s[8:9]
	s_mov_b32 s92, s57
	s_cbranch_vccnz .LBB0_601
	s_mov_b32 s90, 0
	v_cmp_le_u32_e32 vcc, v2, v9
	v_addc_co_u32_e32 v1, vcc, 0, v43, vcc
	v_cmp_le_u32_e32 vcc, v2, v121
	v_addc_co_u32_e32 v1, vcc, v1, v1, vcc
	v_cmp_le_u32_e32 vcc, v2, v10
	v_addc_co_u32_e32 v1, vcc, v1, v1, vcc
	v_cmp_le_u32_e32 vcc, v2, v11
	v_addc_co_u32_e32 v1, vcc, v1, v1, vcc

; DI void select_row(const float* SC, unsigned* dmask, int b, int t, int lane) {
;     ...
;     for (int k = 0; k < 8; ++k) {
;         unsigned nib = 0u;
;         if (k < nch) {
;             if (exact) {
; #pragma unroll
;                 for (int e = 0; e < 4; ++e) nib |= (u[k][e] >= T ? 1u : 0u) << e;
;             } else {
;                 unsigned long long bm[4]; int lanes_before = 0, tot = 0;
; #pragma unroll
;                 for (int e = 0; e < 4; ++e) { bm[e] = __ballot(u[k][e] == T); lanes_before += __popcll(bm[e] & ltmask); tot += __popcll(bm[e]); }
;                 int rank = tie_before + lanes_before;
; #pragma unroll
;                 for (int e = 0; e < 4; ++e) { const bool eq = (u[k][e] == T); const bool s = (u[k][e] > T) || (eq && rank < need); nib |= (s ? 1u : 0u) << e; rank += eq ? 1 : 0; }
;                 tie_before += tot;
;             }
;         }
;         unsigned val = nib << (4 * (lane & 7));
;         val |= (unsigned)__builtin_amdgcn_update_dpp(0, (int)val, 0x101, 0xf, 0xf, true); val |= (unsigned)__builtin_amdgcn_update_dpp(0, (int)val, 0x102, 0xf, 0xf, true); val |= (unsigned)__builtin_amdgcn_update_dpp(0, (int)val, 0x104, 0xf, 0xf, true);
;         if ((lane & 7) == 0) dm[8 * k + (lane >> 3)] = val;
.LBB0_605:
	s_andn2_b64 vcc, exec, s[8:9]
	s_cbranch_vccnz .LBB0_607
	v_cmp_le_u32_e32 vcc, v2, v5
	v_addc_co_u32_e32 v1, vcc, 0, v43, vcc
	v_cmp_le_u32_e32 vcc, v2, v8
	v_addc_co_u32_e32 v1, vcc, v1, v1, vcc
	v_cmp_le_u32_e32 vcc, v2, v6
	v_addc_co_u32_e32 v1, vcc, v1, v1, vcc
	v_cmp_le_u32_e32 vcc, v2, v7
	v_addc_co_u32_e32 v1, vcc, v1, v1, vcc
	v_mov_b32_e32 v4, s90

; DI void select_row(const float* SC, unsigned* dmask, int b, int t, int lane) {
;     ...
;     for (int k = 0; k < 8; ++k) {
;         unsigned nib = 0u;
;         if (k < nch) {
;             if (exact) {
; #pragma unroll
;                 for (int e = 0; e < 4; ++e) nib |= (u[k][e] >= T ? 1u : 0u) << e;
;             } else {
;                 unsigned long long bm[4]; int lanes_before = 0, tot = 0;
; #pragma unroll
;                 for (int e = 0; e < 4; ++e) { bm[e] = __ballot(u[k][e] == T); lanes_before += __popcll(bm[e] & ltmask); tot += __popcll(bm[e]); }
;                 int rank = tie_before + lanes_before;
; #pragma unroll
;                 for (int e = 0; e < 4; ++e) { const bool eq = (u[k][e] == T); const bool s = (u[k][e] > T) || (eq && rank < need); nib |= (s ? 1u : 0u) << e; rank += eq ? 1 : 0; }
;                 tie_before += tot;
;             }
;         }
;         unsigned val = nib << (4 * (lane & 7));
;         val |= (unsigned)__builtin_amdgcn_update_dpp(0, (int)val, 0x101, 0xf, 0xf, true); val |= (unsigned)__builtin_amdgcn_update_dpp(0, (int)val, 0x102, 0xf, 0xf, true); val |= (unsigned)__builtin_amdgcn_update_dpp(0, (int)val, 0x104, 0xf, 0xf, true);
;         if ((lane & 7) == 0) dm[8 * k + (lane >> 3)] = val;
.LBB0_612:
	s_andn2_b64 vcc, exec, s[8:9]
	s_cbranch_vccnz .LBB0_614
	v_cmp_le_u32_e32 vcc, v2, v42
	v_addc_co_u32_e32 v1, vcc, 0, v43, vcc
	v_cmp_le_u32_e32 vcc, v2, v32
	v_addc_co_u32_e32 v1, vcc, v1, v1, vcc
	v_cmp_le_u32_e32 vcc, v2, v41
	v_addc_co_u32_e32 v1, vcc, v1, v1, vcc
	v_cmp_le_u32_e32 vcc, v2, v33
	v_addc_co_u32_e32 v1, vcc, v1, v1, vcc
	v_mov_b32_e32 v5, v4

; DI void select_row(const float* SC, unsigned* dmask, int b, int t, int lane) {
;     ...
;     for (int k = 0; k < 8; ++k) {
;         unsigned nib = 0u;
;         if (k < nch) {
;             if (exact) {
; #pragma unroll
;                 for (int e = 0; e < 4; ++e) nib |= (u[k][e] >= T ? 1u : 0u) << e;
;             } else {
;                 unsigned long long bm[4]; int lanes_before = 0, tot = 0;
; #pragma unroll
;                 for (int e = 0; e < 4; ++e) { bm[e] = __ballot(u[k][e] == T); lanes_before += __popcll(bm[e] & ltmask); tot += __popcll(bm[e]); }
;                 int rank = tie_before + lanes_before;
; #pragma unroll
;                 for (int e = 0; e < 4; ++e) { const bool eq = (u[k][e] == T); const bool s = (u[k][e] > T) || (eq && rank < need); nib |= (s ? 1u : 0u) << e; rank += eq ? 1 : 0; }
;                 tie_before += tot;
;             }
;         }
;         unsigned val = nib << (4 * (lane & 7));
;         val |= (unsigned)__builtin_amdgcn_update_dpp(0, (int)val, 0x101, 0xf, 0xf, true); val |= (unsigned)__builtin_amdgcn_update_dpp(0, (int)val, 0x102, 0xf, 0xf, true); val |= (unsigned)__builtin_amdgcn_update_dpp(0, (int)val, 0x104, 0xf, 0xf, true);
;         if ((lane & 7) == 0) dm[8 * k + (lane >> 3)] = val;
.LBB0_620:
	s_andn2_b64 vcc, exec, s[8:9]
	s_cbranch_vccnz .LBB0_622
	v_cmp_le_u32_e32 vcc, v2, v31
	v_addc_co_u32_e32 v1, vcc, 0, v43, vcc
	v_cmp_le_u32_e32 vcc, v2, v28
	v_addc_co_u32_e32 v1, vcc, v1, v1, vcc
	v_cmp_le_u32_e32 vcc, v2, v30
	v_addc_co_u32_e32 v1, vcc, v1, v1, vcc
	v_cmp_le_u32_e32 vcc, v2, v29
	v_addc_co_u32_e32 v1, vcc, v1, v1, vcc
	v_mov_b32_e32 v5, v4

; DI void select_row(const float* SC, unsigned* dmask, int b, int t, int lane) {
;     ...
;     for (int k = 0; k < 8; ++k) {
;         unsigned nib = 0u;
;         if (k < nch) {
;             if (exact) {
; #pragma unroll
;                 for (int e = 0; e < 4; ++e) nib |= (u[k][e] >= T ? 1u : 0u) << e;
;             } else {
;                 unsigned long long bm[4]; int lanes_before = 0, tot = 0;
; #pragma unroll
;                 for (int e = 0; e < 4; ++e) { bm[e] = __ballot(u[k][e] == T); lanes_before += __popcll(bm[e] & ltmask); tot += __popcll(bm[e]); }
;                 int rank = tie_before + lanes_before;
; #pragma unroll
;                 for (int e = 0; e < 4; ++e) { const bool eq = (u[k][e] == T); const bool s = (u[k][e] > T) || (eq && rank < need); nib |= (s ? 1u : 0u) << e; rank += eq ? 1 : 0; }
;                 tie_before += tot;
;             }
;         }
;         unsigned val = nib << (4 * (lane & 7));
;         val |= (unsigned)__builtin_amdgcn_update_dpp(0, (int)val, 0x101, 0xf, 0xf, true); val |= (unsigned)__builtin_amdgcn_update_dpp(0, (int)val, 0x102, 0xf, 0xf, true); val |= (unsigned)__builtin_amdgcn_update_dpp(0, (int)val, 0x104, 0xf, 0xf, true);
;         if ((lane & 7) == 0) dm[8 * k + (lane >> 3)] = val;
.LBB0_628:
	s_andn2_b64 vcc, exec, s[8:9]
	s_cbranch_vccnz .LBB0_630
	v_cmp_le_u32_e32 vcc, v2, v27
	v_addc_co_u32_e32 v1, vcc, 0, v43, vcc
	v_cmp_le_u32_e32 vcc, v2, v26
	v_addc_co_u32_e32 v1, vcc, v1, v1, vcc
	v_cmp_le_u32_e32 vcc, v2, v25
	v_addc_co_u32_e32 v1, vcc, v1, v1, vcc
	v_cmp_le_u32_e32 vcc, v2, v24
	v_addc_co_u32_e32 v1, vcc, v1, v1, vcc
	v_mov_b32_e32 v5, v4

; DI void select_row(const float* SC, unsigned* dmask, int b, int t, int lane) {
;     ...
;     for (int k = 0; k < 8; ++k) {
;         unsigned nib = 0u;
;         if (k < nch) {
;             if (exact) {
; #pragma unroll
;                 for (int e = 0; e < 4; ++e) nib |= (u[k][e] >= T ? 1u : 0u) << e;
;             } else {
;                 unsigned long long bm[4]; int lanes_before = 0, tot = 0;
; #pragma unroll
;                 for (int e = 0; e < 4; ++e) { bm[e] = __ballot(u[k][e] == T); lanes_before += __popcll(bm[e] & ltmask); tot += __popcll(bm[e]); }
;                 int rank = tie_before + lanes_before;
; #pragma unroll
;                 for (int e = 0; e < 4; ++e) { const bool eq = (u[k][e] == T); const bool s = (u[k][e] > T) || (eq && rank < need); nib |= (s ? 1u : 0u) << e; rank += eq ? 1 : 0; }
;                 tie_before += tot;
;             }
;         }
;         unsigned val = nib << (4 * (lane & 7));
;         val |= (unsigned)__builtin_amdgcn_update_dpp(0, (int)val, 0x101, 0xf, 0xf, true); val |= (unsigned)__builtin_amdgcn_update_dpp(0, (int)val, 0x102, 0xf, 0xf, true); val |= (unsigned)__builtin_amdgcn_update_dpp(0, (int)val, 0x104, 0xf, 0xf, true);
;         if ((lane & 7) == 0) dm[8 * k + (lane >> 3)] = val;
.LBB0_636:
	s_andn2_b64 vcc, exec, s[8:9]
	s_cbranch_vccnz .LBB0_638
	v_cmp_le_u32_e32 vcc, v2, v23
	v_addc_co_u32_e32 v1, vcc, 0, v43, vcc
	v_cmp_le_u32_e32 vcc, v2, v18
	v_addc_co_u32_e32 v1, vcc, v1, v1, vcc
	v_cmp_le_u32_e32 vcc, v2, v22
	v_addc_co_u32_e32 v1, vcc, v1, v1, vcc
	v_cmp_le_u32_e32 vcc, v2, v21
	v_addc_co_u32_e32 v1, vcc, v1, v1, vcc
	v_mov_b32_e32 v5, v4

; DI void select_row(const float* SC, unsigned* dmask, int b, int t, int lane) {
;     ...
;     for (int k = 0; k < 8; ++k) {
;         unsigned nib = 0u;
;         if (k < nch) {
;             if (exact) {
; #pragma unroll
;                 for (int e = 0; e < 4; ++e) nib |= (u[k][e] >= T ? 1u : 0u) << e;
;             } else {
;                 unsigned long long bm[4]; int lanes_before = 0, tot = 0;
; #pragma unroll
;                 for (int e = 0; e < 4; ++e) { bm[e] = __ballot(u[k][e] == T); lanes_before += __popcll(bm[e] & ltmask); tot += __popcll(bm[e]); }
;                 int rank = tie_before + lanes_before;
; #pragma unroll
;                 for (int e = 0; e < 4; ++e) { const bool eq = (u[k][e] == T); const bool s = (u[k][e] > T) || (eq && rank < need); nib |= (s ? 1u : 0u) << e; rank += eq ? 1 : 0; }
;                 tie_before += tot;
;             }
;         }
;         unsigned val = nib << (4 * (lane & 7));
;         val |= (unsigned)__builtin_amdgcn_update_dpp(0, (int)val, 0x101, 0xf, 0xf, true); val |= (unsigned)__builtin_amdgcn_update_dpp(0, (int)val, 0x102, 0xf, 0xf, true); val |= (unsigned)__builtin_amdgcn_update_dpp(0, (int)val, 0x104, 0xf, 0xf, true);
;         if ((lane & 7) == 0) dm[8 * k + (lane >> 3)] = val;
.LBB0_644:
	s_andn2_b64 vcc, exec, s[8:9]
	s_cbranch_vccnz .LBB0_646
	v_cmp_le_u32_e32 vcc, v2, v20
	v_addc_co_u32_e32 v1, vcc, 0, v43, vcc
	v_cmp_le_u32_e32 vcc, v2, v19
	v_addc_co_u32_e32 v1, vcc, v1, v1, vcc
	v_cmp_le_u32_e32 vcc, v2, v16
	v_addc_co_u32_e32 v1, vcc, v1, v1, vcc
	v_cmp_le_u32_e32 vcc, v2, v15
	v_addc_co_u32_e32 v1, vcc, v1, v1, vcc
	v_mov_b32_e32 v5, v4

; DI void select_row(const float* SC, unsigned* dmask, int b, int t, int lane) {
;     ...
;     for (int k = 0; k < 8; ++k) {
;         unsigned nib = 0u;
;         if (k < nch) {
;             if (exact) {
; #pragma unroll
;                 for (int e = 0; e < 4; ++e) nib |= (u[k][e] >= T ? 1u : 0u) << e;
;             } else {
;                 unsigned long long bm[4]; int lanes_before = 0, tot = 0;
; #pragma unroll
;                 for (int e = 0; e < 4; ++e) { bm[e] = __ballot(u[k][e] == T); lanes_before += __popcll(bm[e] & ltmask); tot += __popcll(bm[e]); }
;                 int rank = tie_before + lanes_before;
; #pragma unroll
;                 for (int e = 0; e < 4; ++e) { const bool eq = (u[k][e] == T); const bool s = (u[k][e] > T) || (eq && rank < need); nib |= (s ? 1u : 0u) << e; rank += eq ? 1 : 0; }
;                 tie_before += tot;
;             }
;         }
;         unsigned val = nib << (4 * (lane & 7));
;         val |= (unsigned)__builtin_amdgcn_update_dpp(0, (int)val, 0x101, 0xf, 0xf, true); val |= (unsigned)__builtin_amdgcn_update_dpp(0, (int)val, 0x102, 0xf, 0xf, true); val |= (unsigned)__builtin_amdgcn_update_dpp(0, (int)val, 0x104, 0xf, 0xf, true);
;         if ((lane & 7) == 0) dm[8 * k + (lane >> 3)] = val;
.LBB0_652:
	s_andn2_b64 vcc, exec, s[8:9]
	s_cbranch_vccnz .LBB0_654
	v_cmp_le_u32_e32 vcc, v2, v17
	v_addc_co_u32_e32 v1, vcc, 0, v43, vcc
	v_cmp_le_u32_e32 vcc, v2, v12
	v_addc_co_u32_e32 v1, vcc, v1, v1, vcc
	v_cmp_le_u32_e32 vcc, v2, v14
	v_addc_co_u32_e32 v1, vcc, v1, v1, vcc
	v_cmp_le_u32_e32 vcc, v2, v13
	v_addc_co_u32_e32 v1, vcc, v1, v1, vcc
